# P4 tail: deferred w_ff1 conversion on 4 of 8 waves of the non-GEMM workgroups (less HBM contention for the sample rows' gated GEMM, the tail's critical path: 33.3 -> 29.5 us by in-kernel stopwatch)
# speedup vs baseline: 1.0018x; 1.0013x over previous
.LBB0_589:
	s_cmp_gt_i32 s96, 16
	s_cselect_b32 s4, 16, 0
	s_cmp_lt_i32 s2, s4
	s_cbranch_scc1 .LBB0_605
	s_sub_i32 s0, s2, s4
	s_lshl_b32 s0, s0, 2
	v_readlane_b32 s1, v255, 5
	s_add_i32 s0, s0, s1
	s_cmp_gt_u32 s1, 3
	s_cbranch_scc1 .LBB0_605
	s_cmpk_gt_u32 s0, 0x1fff
	s_cbranch_scc1 .LBB0_605
	v_and_b32_e32 v2, 28, v160
	v_readlane_b32 s3, v255, 5
	v_lshlrev_b32_e32 v18, 2, v2
	v_lshlrev_b32_e32 v2, 3, v0
	s_lshl_b32 s3, s3, 14
	v_lshrrev_b32_e32 v20, 3, v170
	v_and_b32_e32 v2, 56, v2
	s_add_i32 s3, s3, 0
	v_mul_u32_u24_e32 v3, 0x84, v2
	v_lshlrev_b32_e32 v4, 2, v20
	v_add_u32_e32 v25, s3, v18
	v_add3_u32 v24, s3, v3, v4
	s_lshr_b32 s3, s3, 14
	v_mul_u32_u24_e32 v26, 0x84, v20
	v_mov_b32_e32 v3, 0
	s_sub_i32 s6, s2, s4
	s_lshl2_add_u32 s3, s6, s3
	s_sub_i32 s1, s96, s4
	v_lshlrev_b32_e32 v2, 1, v2
	v_mov_b32_e32 v19, v3
	s_lshl_b32 s3, s3, 5
	s_lshl_b32 s6, s96, 7
	s_lshl_b32 s4, s4, 7
	v_add_u32_e32 v25, v25, v26
	s_lshl_b32 s1, s1, 2
	s_mov_b32 s5, 0
	v_or_b32_e32 v21, 8, v20
	v_or_b32_e32 v22, 16, v20
	v_or_b32_e32 v23, 24, v20
	v_lshl_add_u64 v[4:5], s[78:79], 0, v[2:3]
	s_waitcnt vmcnt(1)
	v_lshl_add_u64 v[6:7], s[82:83], 0, v[2:3]
	v_lshl_add_u64 v[8:9], s[80:81], 0, v[2:3]
	s_waitcnt vmcnt(0)
	v_lshl_add_u64 v[10:11], s[76:77], 0, v[2:3]
	v_lshl_add_u64 v[12:13], s[18:19], 0, v[18:19]
	v_lshl_add_u64 v[14:15], s[46:47], 0, v[18:19]
	v_lshl_add_u64 v[16:17], s[48:49], 0, v[18:19]
	v_lshl_add_u64 v[18:19], s[36:37], 0, v[18:19]
	s_add_i32 s3, s3, 0x58000
	s_sub_i32 s8, s6, s4
	s_mov_b32 s9, 0x40000
	v_add_u32_e32 v26, 0x420, v25
	v_add_u32_e32 v27, 0x428, v25
	v_add_u32_e32 v28, 0x840, v25
	v_add_u32_e32 v29, 0x848, v25
	v_add_u32_e32 v30, 0xc60, v25
	v_add_u32_e32 v31, 0xc68, v25
	v_add_u32_e32 v32, 0x1080, v25
	v_add_u32_e32 v33, 0x1088, v25
	v_add_u32_e32 v34, 0x14a0, v25
	v_add_u32_e32 v35, 0x14a8, v25
	v_add_u32_e32 v36, 0x18c0, v25
	v_add_u32_e32 v37, 0x18c8, v25
	v_add_u32_e32 v38, 0x1ce0, v25
	v_add_u32_e32 v39, 0x1ce8, v25
	s_movk_i32 s10, 0x7fff
	s_mov_b32 s11, 0xffff0000
	s_branch .LBB0_593
